# strategy 4 A/B: static s_setprio 1 for waves 0-3 (older half) during GEMM phases, no per-segment flips
# baseline (speedup 1.0000x reference)
; #define LAS __attribute__((address_space(3)))
; __device__ __forceinline__ void run_phase(KParams p, int ph, LAS unsigned char* lds) {
;     if (ph == 0) { prepass(p, lds); return; }
;     if (ph == NPHASE - 1) { final_norm_phase(p); return; }
;     const int l = (ph - 1) / NPL, s = (ph - 1) % NPL;
;     const int Mx = (l == 0) ? MT : ML;
;     const bf16_t* wt = p->wt + (size_t)l * WT_LAYER;
;     const float* modl = p->mod + (size_t)l * 9 * 12288;
;     switch (s) {
.LBB0_22:
	s_add_i32 s8, s6, -1
	s_ashr_i32 s9, s8, 31
	s_lshr_b32 s9, s9, 29
	s_add_i32 s9, s8, s9
	s_ashr_i32 s12, s9, 3
	s_and_b32 s9, s9, -8
	s_sub_i32 s98, s8, s9
	s_mov_b32 s101, 0
	s_cmp_eq_u32 s98, 1
	s_cselect_b32 s101, 1, s101
	s_cmp_eq_u32 s98, 6
	s_cselect_b32 s101, 1, s101
	s_cmp_eq_u32 s98, 4
	s_cselect_b32 s101, 1, s101
	s_cmp_eq_u32 s98, 7
	s_cselect_b32 s101, 1, s101
	v_readfirstlane_b32 s100, v208
	s_nop 3
	s_lshr_b32 s100, s100, 8
	s_xor_b32 s100, s100, 1
	s_and_b32 s100, s100, s101
	s_cmp_eq_u32 s100, 0
	s_cbranch_scc1 .Lsprio_skip
	s_setprio 1
